# adds: ret_out and ret_kv load ldf/ldb with scalar loads so the loop top no longer drains the previous unit's stores
# speedup vs baseline: 1.0057x; 1.0057x over previous
; #define LAS __attribute__((address_space(3)))
; __device__ __forceinline__ float fexp(float x) { return __builtin_amdgcn_exp2f(1.4426950408889634f * x); }
; #define R1_ISSUE(u_) do { const bf16_t* src_ = proj + (size_t)(((u_) >> 2) * 128 + stok) * DIN + 1280 + ((u_) & 3) * 128 + sdch * 8; \
;         _Pragma("unroll") for (int i_ = 0; i_ < 4; ++i_) { pk[i_] = *(const u32x4*)(src_ + (size_t)i_ * 32 * DIN); pv[i_] = *(const u32x4*)(src_ + 512 + (size_t)i_ * 32 * DIN); } } while (0)
; __device__ __forceinline__ void ret_kv_phase(const Params& p, LAS unsigned char* lds, int G) {
;     const int tid = threadIdx.x, lane = tid & 63, wave = tid >> 6, fr = lane & 15, fq = lane >> 4;
;     const bf16_t* proj = (const bf16_t*)(p.ws + WS_HID); bf16_t* kvbuf = (bf16_t*)p.out;
;     LAS bf16_t* Vl = (LAS bf16_t*)lds; LAS bf16_t* Kf = (LAS bf16_t*)(lds + 34816); LAS bf16_t* Kb = (LAS bf16_t*)(lds + 69632);
;     const int stok = tid >> 4, sdch = tid & 15;
;     const int trb = (8 * fq + (fr >> 2)) * 136 + 4 * (fr & 3);
;     u32x4 pk[4], pv[4];
;     ...
;     int unit = blockIdx.x;
;     if (unit < (T / 128) * 4) R1_ISSUE(unit);
;     for (; unit < (T / 128) * 4; unit += G) {
;         const int c = unit >> 2, h = unit & 3;
;         const float ldf = p.in[10][h], ldb = p.in[11][h];
;         __syncthreads();
; #pragma unroll
;         for (int i = 0; i < 4; ++i) {
;             const int tok = stok + 32 * i; const float wf = fexp(ldf * (float)(127 - tok)), wb = fexp(ldb * (float)tok);
.LBB0_574:
	v_lshrrev_b32_e32 v36, 4, v198
	s_cmpk_gt_i32 s90, 0x5ff
	s_waitcnt vmcnt(0)
	s_barrier
	s_cbranch_scc1 .LBB0_579
	s_add_u32 s6, s92, 0xf000000
	s_addc_u32 s7, s93, 0
	s_lshl_b32 s0, s90, 5
	s_and_b32 s0, s0, 0xffffff80
	v_or_b32_e32 v2, s0, v36
	s_movk_i32 s14, 0x1600
	v_mov_b64_e32 v[0:1], s[6:7]
	v_mad_i64_i32 v[0:1], s[0:1], v2, s14, v[0:1]
	s_lshl_b32 s0, s90, 8
	s_and_b32 s8, s0, 0x300
	s_mov_b32 s9, 0
	v_lshl_add_u64 v[0:1], v[0:1], 0, s[8:9]
	v_mov_b32_e32 v33, 0
	v_lshlrev_b32_e32 v32, 4, v199
	v_lshl_add_u64 v[24:25], v[0:1], 0, v[32:33]
	s_mov_b32 s0, 0x2c000
	v_add_co_u32_e32 v16, vcc, s0, v24
	s_mov_b32 s0, 0x58000
	s_nop 0
	v_addc_co_u32_e32 v17, vcc, 0, v25, vcc
	v_add_co_u32_e32 v26, vcc, s0, v24
	s_mov_b32 s0, 0x84000
	s_nop 0
	v_addc_co_u32_e32 v27, vcc, 0, v25, vcc
	v_add_co_u32_e32 v34, vcc, s0, v24
	global_load_dwordx4 v[0:3], v[24:25], off offset:2560
	global_load_dwordx4 v[4:7], v[24:25], off offset:3584
	v_addc_co_u32_e32 v35, vcc, 0, v25, vcc
	global_load_dwordx4 v[8:11], v[16:17], off offset:2560
	global_load_dwordx4 v[12:15], v[16:17], off offset:3584
	s_nop 0
	global_load_dwordx4 v[16:19], v[26:27], off offset:2560
	global_load_dwordx4 v[20:23], v[26:27], off offset:3584
	s_nop 0
	global_load_dwordx4 v[24:27], v[34:35], off offset:2560
	global_load_dwordx4 v[28:31], v[34:35], off offset:3584
	s_add_i32 s0, 0, 0x11000
	v_lshrrev_b32_e32 v35, 5, v198
	s_movk_i32 s1, 0x100
	s_add_i32 s2, 0, 0x8800
	v_mul_u32_u24_e32 v34, 0x88, v201
	v_and_b32_e32 v51, 6, v35
	v_mov_b32_e32 v35, s0
	v_mov_b32_e32 v37, s2
	v_cmp_gt_u32_e32 vcc, s1, v198
	v_add_lshl_u32 v34, v34, v200, 1
	v_add_u32_e32 v53, 0, v34
	v_cndmask_b32_e32 v35, v35, v37, vcc
	v_add_u32_e32 v37, v35, v34
	v_xor_b32_e32 v34, 0x7f, v36
	v_cvt_f32_ubyte0_e32 v38, v34
	v_mul_u32_u24_e32 v34, 0x88, v36
	v_lshlrev_b32_e32 v34, 1, v34
	v_add3_u32 v40, 0, v32, v34
	v_add3_u32 v41, s0, v32, v34
	v_add_u32_e32 v32, 32, v36
	v_cvt_f32_ubyte0_e32 v43, v32
	v_or_b32_e32 v32, 64, v36
	v_sub_u32_e32 v34, 0x5f, v36
	v_cvt_f32_ubyte0_e32 v46, v32
	v_add_u32_e32 v32, 0x60, v36
	v_cvt_f32_ubyte0_e32 v42, v34
	v_xor_b32_e32 v34, 63, v36
	v_cvt_f32_ubyte0_e32 v49, v32
	s_ashr_i32 s91, s90, 31
	v_lshlrev_b32_e32 v32, 7, v198
	v_cvt_f32_ubyte0_e32 v45, v34
	v_sub_u32_e32 v34, 31, v36
	s_load_dwordx2 s[10:11], s[88:89], 0x90
	s_load_dwordx4 s[0:3], s[88:89], 0x50
	s_lshl_b64 s[12:13], s[90:91], 16
	v_and_b32_e32 v32, 0x18000, v32
	v_cvt_f32_i32_e32 v48, v34
	v_lshl_add_u64 v[34:35], s[12:13], 0, v[32:33]
	v_lshrrev_b32_e32 v32, 1, v198
	v_lshlrev_b32_e32 v55, 8, v199
	v_lshlrev_b32_e32 v54, 5, v51
	v_and_b32_e32 v32, 24, v32
	v_lshl_or_b32 v51, v51, 12, v55
	v_or3_b32 v34, v34, v32, v51
	s_waitcnt lgkmcnt(0)
	v_lshl_add_u64 v[34:35], s[10:11], 0, v[34:35]
	s_mov_b64 s[10:11], 0x1000
	v_lshlrev_b32_e32 v52, 3, v199
	v_lshl_add_u64 v[34:35], v[34:35], 0, s[10:11]
	s_ashr_i32 s11, s86, 31
	s_mov_b32 s10, s86
	s_add_i32 s8, s90, s86
	v_cvt_f32_ubyte0_e32 v39, v36
	v_add_u32_e32 v44, 0x2200, v41
	v_add_u32_e32 v47, 0x4400, v41
	v_add_u32_e32 v50, 0x6600, v41
	s_lshl_b64 s[10:11], s[10:11], 16
	s_lshl_b32 s15, s8, 7
	s_lshl_b32 s16, s86, 7
	s_lshl_b32 s17, s8, 5
	s_lshl_b32 s18, s86, 5
	v_lshlrev_b32_e32 v32, 1, v52
	v_add_u32_e32 v51, v53, v54
	s_mov_b32 s19, s90
	s_waitcnt vmcnt(0)
	s_branch .LBB0_577

; __device__ __forceinline__ unsigned cvt_pk_bf16(float lo, float hi) { unsigned r; asm volatile("v_cvt_pk_bf16_f32 %0, %1, %2" : "=v"(r) : "v"(lo), "v"(hi)); return r; }
; #define LAS __attribute__((address_space(3)))
; __device__ __forceinline__ unsigned cvt_pk_bf16(float lo, float hi) { f32x2_t v = {lo, hi}; bf16x2_t b = __builtin_convertvector(v, bf16x2_t); return __builtin_bit_cast(unsigned, b); }
; __device__ __forceinline__ float fexp(float x) { return __builtin_amdgcn_exp2f(1.4426950408889634f * x); }
; #define R1_ISSUE(u_) do { const bf16_t* src_ = proj + (size_t)(((u_) >> 2) * 128 + stok) * DIN + 1280 + ((u_) & 3) * 128 + sdch * 8; \
;         _Pragma("unroll") for (int i_ = 0; i_ < 4; ++i_) { pk[i_] = *(const u32x4*)(src_ + (size_t)i_ * 32 * DIN); pv[i_] = *(const u32x4*)(src_ + 512 + (size_t)i_ * 32 * DIN); } } while (0)
; __device__ __forceinline__ void ret_kv_phase(const Params& p, LAS unsigned char* lds, int G) {
;     ...
;     for (; unit < (T / 128) * 4; unit += G) {
;         const int c = unit >> 2, h = unit & 3;
;         const float ldf = p.in[10][h], ldb = p.in[11][h];
;         __syncthreads();
; #pragma unroll
;         for (int i = 0; i < 4; ++i) {
;             const int tok = stok + 32 * i; const float wf = fexp(ldf * (float)(127 - tok)), wb = fexp(ldb * (float)tok);
;             const unsigned kw[4] = {pk[i].x, pk[i].y, pk[i].z, pk[i].w}; u32x4 of, ob; unsigned fo[4], bo[4];
; #pragma unroll
;             for (int q = 0; q < 4; ++q) { const float k0 = bf2f((unsigned short)(kw[q] & 0xffffu)), k1 = bf2f((unsigned short)(kw[q] >> 16)); fo[q] = cvt_pk_bf16(k0 * wf, k1 * wf); bo[q] = cvt_pk_bf16(k0 * wb, k1 * wb); }
;             of.x = fo[0]; of.y = fo[1]; of.z = fo[2]; of.w = fo[3]; ob.x = bo[0]; ob.y = bo[1]; ob.z = bo[2]; ob.w = bo[3];
;             *(LAS u32x4*)(Vl + tok * 136 + sdch * 8) = pv[i]; *(LAS u32x4*)(Kf + tok * 136 + sdch * 8) = of; *(LAS u32x4*)(Kb + tok * 136 + sdch * 8) = ob;
;         }
;         __syncthreads();
;         if (unit + G < (T / 128) * 4) R1_ISSUE(unit + G);
.LBB0_577:
	s_and_b32 s8, s19, 3
	s_lshl_b32 s8, s8, 2
	v_mov_b32_e32 v52, s8
	s_load_dword s98, s[0:1], s8
	s_load_dword s99, s[2:3], s8
	s_waitcnt vmcnt(23)
	v_lshlrev_b32_e32 v52, 16, v0
	v_and_b32_e32 v53, 0xffff0000, v0
	v_lshlrev_b32_e32 v54, 16, v1
	v_and_b32_e32 v55, 0xffff0000, v1
	v_lshlrev_b32_e32 v56, 16, v2
	v_and_b32_e32 v57, 0xffff0000, v2
	v_lshlrev_b32_e32 v58, 16, v3
	v_and_b32_e32 v59, 0xffff0000, v3
	s_waitcnt vmcnt(21)
	v_lshlrev_b32_e32 v60, 16, v8
	v_and_b32_e32 v61, 0xffff0000, v8
	v_lshlrev_b32_e32 v62, 16, v9
	v_and_b32_e32 v63, 0xffff0000, v9
	v_lshlrev_b32_e32 v64, 16, v10
	v_and_b32_e32 v65, 0xffff0000, v10
	v_lshlrev_b32_e32 v66, 16, v11
	v_and_b32_e32 v67, 0xffff0000, v11
	s_barrier
	ds_write_b128 v40, v[4:7]
	s_waitcnt vmcnt(20)
	ds_write_b128 v40, v[12:15] offset:8704
	s_waitcnt vmcnt(19)
	v_lshlrev_b32_e32 v70, 16, v17
	v_and_b32_e32 v71, 0xffff0000, v17
	s_add_i32 s19, s19, s86
	s_cmpk_gt_i32 s19, 0x5ff
	v_lshlrev_b32_e32 v68, 16, v16
	v_and_b32_e32 v69, 0xffff0000, v16
	s_cselect_b64 s[12:13], -1, 0
	s_and_b64 vcc, exec, s[12:13]
	s_waitcnt vmcnt(16)
	s_waitcnt lgkmcnt(0)
	v_mul_f32_e32 v72, s98, v38
	v_mul_f32_e32 v73, s99, v39
	v_mul_f32_e32 v74, s98, v42
	v_mul_f32_e32 v75, s99, v43
	v_mul_f32_e32 v72, 0x3fb8aa3b, v72
	v_mul_f32_e32 v73, 0x3fb8aa3b, v73
	v_mul_f32_e32 v76, s98, v45
	v_mul_f32_e32 v78, 0x3fb8aa3b, v74
	v_mul_f32_e32 v75, 0x3fb8aa3b, v75
	v_exp_f32_e32 v72, v72
	v_exp_f32_e32 v74, v73
	v_mul_f32_e32 v77, s99, v46
	v_mul_f32_e32 v79, 0x3fb8aa3b, v76
	v_exp_f32_e32 v76, v78
	v_exp_f32_e32 v78, v75
	v_mul_f32_e32 v77, 0x3fb8aa3b, v77
	v_exp_f32_e32 v80, v79
	v_exp_f32_e32 v82, v77
	v_pk_mul_f32 v[84:85], v[72:73], v[52:53] op_sel_hi:[0,1]
	v_pk_mul_f32 v[88:89], v[72:73], v[54:55] op_sel_hi:[0,1]
	v_pk_mul_f32 v[54:55], v[74:75], v[54:55] op_sel_hi:[0,1]
	v_pk_mul_f32 v[90:91], v[72:73], v[56:57] op_sel_hi:[0,1]
	v_pk_mul_f32 v[72:73], v[72:73], v[58:59] op_sel_hi:[0,1]
	v_pk_mul_f32 v[86:87], v[74:75], v[52:53] op_sel_hi:[0,1]
	v_pk_mul_f32 v[92:93], v[74:75], v[56:57] op_sel_hi:[0,1]
	v_pk_mul_f32 v[74:75], v[74:75], v[58:59] op_sel_hi:[0,1]
	v_pk_mul_f32 v[94:95], v[76:77], v[60:61] op_sel_hi:[0,1]
	v_pk_mul_f32 v[96:97], v[78:79], v[60:61] op_sel_hi:[0,1]
	v_pk_mul_f32 v[98:99], v[76:77], v[62:63] op_sel_hi:[0,1]
	v_pk_mul_f32 v[62:63], v[78:79], v[62:63] op_sel_hi:[0,1]
	v_pk_mul_f32 v[100:101], v[76:77], v[64:65] op_sel_hi:[0,1]
	v_pk_mul_f32 v[102:103], v[78:79], v[64:65] op_sel_hi:[0,1]
	v_pk_mul_f32 v[76:77], v[76:77], v[66:67] op_sel_hi:[0,1]
	v_pk_mul_f32 v[78:79], v[78:79], v[66:67] op_sel_hi:[0,1]
	v_cvt_pk_bf16_f32 v52, v84, v85
	v_cvt_pk_bf16_f32 v53, v88, v89
	v_cvt_pk_bf16_f32 v57, v54, v55
	v_cvt_pk_bf16_f32 v54, v90, v91
	v_cvt_pk_bf16_f32 v55, v72, v73
	v_cvt_pk_bf16_f32 v56, v86, v87
	v_cvt_pk_bf16_f32 v58, v92, v93
	v_cvt_pk_bf16_f32 v59, v74, v75
	v_cvt_pk_bf16_f32 v60, v94, v95
	v_cvt_pk_bf16_f32 v64, v96, v97
	v_cvt_pk_bf16_f32 v61, v98, v99
	v_cvt_pk_bf16_f32 v65, v62, v63
	v_cvt_pk_bf16_f32 v62, v100, v101
	v_cvt_pk_bf16_f32 v66, v102, v103
	v_cvt_pk_bf16_f32 v63, v76, v77
	v_cvt_pk_bf16_f32 v67, v78, v79
	ds_write_b128 v40, v[52:55] offset:34816
	ds_write_b128 v41, v[56:59]
	ds_write_b128 v40, v[60:63] offset:43520
	ds_write_b128 v44, v[64:67]
	v_lshlrev_b32_e32 v52, 16, v18
	v_and_b32_e32 v53, 0xffff0000, v18
	v_pk_mul_f32 v[54:55], v[80:81], v[52:53] op_sel_hi:[0,1]
	v_pk_mul_f32 v[52:53], v[82:83], v[52:53] op_sel_hi:[0,1]
	v_pk_mul_f32 v[108:109], v[80:81], v[70:71] op_sel_hi:[0,1]
	v_pk_mul_f32 v[70:71], v[82:83], v[70:71] op_sel_hi:[0,1]
	v_cvt_pk_bf16_f32 v74, v52, v53
	v_lshlrev_b32_e32 v52, 16, v19
	v_and_b32_e32 v53, 0xffff0000, v19
	v_cvt_pk_bf16_f32 v73, v70, v71
	v_cvt_pk_bf16_f32 v70, v54, v55
	v_pk_mul_f32 v[54:55], v[80:81], v[52:53] op_sel_hi:[0,1]
	v_pk_mul_f32 v[52:53], v[82:83], v[52:53] op_sel_hi:[0,1]
	v_cvt_pk_bf16_f32 v75, v52, v53
	v_mul_f32_e32 v52, s98, v48
	v_mul_f32_e32 v52, 0x3fb8aa3b, v52
	v_exp_f32_e32 v60, v52
	v_mul_f32_e32 v52, s99, v49
	v_mul_f32_e32 v52, 0x3fb8aa3b, v52
	v_exp_f32_e32 v62, v52
	v_cvt_pk_bf16_f32 v71, v54, v55
	v_lshlrev_b32_e32 v54, 16, v24
	v_and_b32_e32 v55, 0xffff0000, v24
	v_pk_mul_f32 v[52:53], v[60:61], v[54:55] op_sel_hi:[0,1]
	v_pk_mul_f32 v[54:55], v[62:63], v[54:55] op_sel_hi:[0,1]
	v_cvt_pk_bf16_f32 v56, v54, v55
	v_lshlrev_b32_e32 v54, 16, v25
	v_and_b32_e32 v55, 0xffff0000, v25
	v_pk_mul_f32 v[58:59], v[60:61], v[54:55] op_sel_hi:[0,1]
	v_cvt_pk_bf16_f32 v52, v52, v53
	v_cvt_pk_bf16_f32 v53, v58, v59
	v_pk_mul_f32 v[54:55], v[62:63], v[54:55] op_sel_hi:[0,1]
	v_lshlrev_b32_e32 v58, 16, v26
	v_and_b32_e32 v59, 0xffff0000, v26
	v_lshlrev_b32_e32 v64, 16, v27
	v_and_b32_e32 v65, 0xffff0000, v27
	v_cvt_pk_bf16_f32 v57, v54, v55
	v_pk_mul_f32 v[54:55], v[60:61], v[58:59] op_sel_hi:[0,1]
	v_pk_mul_f32 v[60:61], v[60:61], v[64:65] op_sel_hi:[0,1]
	v_pk_mul_f32 v[104:105], v[80:81], v[68:69] op_sel_hi:[0,1]
	v_pk_mul_f32 v[106:107], v[82:83], v[68:69] op_sel_hi:[0,1]
	v_cvt_pk_bf16_f32 v54, v54, v55
	v_pk_mul_f32 v[58:59], v[62:63], v[58:59] op_sel_hi:[0,1]
	v_cvt_pk_bf16_f32 v55, v60, v61
	v_pk_mul_f32 v[60:61], v[62:63], v[64:65] op_sel_hi:[0,1]
	v_cvt_pk_bf16_f32 v68, v104, v105
	v_cvt_pk_bf16_f32 v72, v106, v107
	v_cvt_pk_bf16_f32 v69, v108, v109
	ds_write_b128 v40, v[20:23] offset:17408
	ds_write_b128 v40, v[68:71] offset:52224
	ds_write_b128 v47, v[72:75]
	v_cvt_pk_bf16_f32 v58, v58, v59
	v_cvt_pk_bf16_f32 v59, v60, v61
	ds_write_b128 v40, v[28:31] offset:26112
	ds_write_b128 v40, v[52:55] offset:60928
	ds_write_b128 v50, v[56:59]
	s_waitcnt lgkmcnt(0)
	s_barrier
	s_cbranch_vccnz .LBB0_576
	s_and_b32 s8, s17, 0xffffff80
	v_or_b32_e32 v2, s8, v36
	v_mov_b64_e32 v[0:1], s[6:7]
	s_and_b32 s8, s15, 0x180
	v_mad_i64_i32 v[0:1], s[20:21], v2, s14, v[0:1]
	s_lshl_b32 s8, s8, 1
	v_lshl_add_u64 v[0:1], v[0:1], 0, s[8:9]
	v_lshl_add_u64 v[24:25], v[0:1], 0, v[32:33]
	v_add_co_u32_e32 v16, vcc, 0x2c000, v24
	global_load_dwordx4 v[0:3], v[24:25], off offset:2560
	global_load_dwordx4 v[4:7], v[24:25], off offset:3584
	v_addc_co_u32_e32 v17, vcc, 0, v25, vcc
	v_add_co_u32_e32 v26, vcc, 0x58000, v24
	global_load_dwordx4 v[8:11], v[16:17], off offset:2560
	global_load_dwordx4 v[12:15], v[16:17], off offset:3584
	v_addc_co_u32_e32 v27, vcc, 0, v25, vcc
	v_add_co_u32_e32 v52, vcc, 0x84000, v24
	global_load_dwordx4 v[16:19], v[26:27], off offset:2560
	global_load_dwordx4 v[20:23], v[26:27], off offset:3584
	v_addc_co_u32_e32 v53, vcc, 0, v25, vcc
	global_load_dwordx4 v[24:27], v[52:53], off offset:2560
	global_load_dwordx4 v[28:31], v[52:53], off offset:3584
	s_branch .LBB0_576

; #define LAS __attribute__((address_space(3)))
; #define R3_ISSUE(u_) do { const bf16_t* src_ = proj + (size_t)(((u_) >> 2) * 128 + stok) * DIN + 768 + ((u_) & 3) * 128 + sdch * 8; \
;         _Pragma("unroll") for (int i_ = 0; i_ < 4; ++i_) { pq[i_] = *(const u32x4*)(src_ + (size_t)i_ * 32 * DIN); pk[i_] = *(const u32x4*)(src_ + 512 + (size_t)i_ * 32 * DIN); pv[i_] = *(const u32x4*)(src_ + 1024 + (size_t)i_ * 32 * DIN); } } while (0)
; __device__ __forceinline__ void ret_out_phase(const Params& p, LAS unsigned char* lds, int G) {
;     const int tid = threadIdx.x, lane = tid & 63, wave = tid >> 6, fr = lane & 15, fq = lane >> 4;
;     const bf16_t* proj = (const bf16_t*)(p.ws + WS_HID); const bf16_t* kvbuf = (const bf16_t*)p.out; bf16_t* mix = (bf16_t*)(p.ws + WS_ACTB);
;     LAS bf16_t* Ql = (LAS bf16_t*)lds; LAS bf16_t* Kl = (LAS bf16_t*)(lds + 34816); LAS bf16_t* Vl = (LAS bf16_t*)(lds + 69632); LAS bf16_t* Pl = (LAS bf16_t*)(lds + 104448);
;     const int stok = tid >> 4, sdch = tid & 15;
;     const int trb = (8 * fq + (fr >> 2)) * 136 + 4 * (fr & 3);
;     const int il = 16 * wave + fr;
;     u32x4 pq[4], pk[4], pv[4];
;     ...
;     int unit = blockIdx.x;
;     if (unit < (T / 128) * 4) R3_ISSUE(unit);
;     ...
; #pragma unroll
;                 for (int e = 0; e < 4; ++e) { const int j = 16 * n + 4 * fq + e, dlt = il - j; const float coef = dlt > 0 ? ldf2 : ldb2; const float ex = __builtin_amdgcn_exp2f(coef * (float)(dlt > 0 ? dlt : -dlt)); pvv[e] = s[n][e] * (dlt == 0 ? 2.0f : ex); }
.LBB0_694:
	s_load_dwordx2 s[2:3], s[88:89], 0xa0
	s_waitcnt lgkmcnt(0)
	s_cmp_lt_i32 s2, 7
	s_cselect_b64 s[2:3], -1, 0
	s_and_b64 s[0:1], s[2:3], s[0:1]
	v_writelane_b32 v247, s0, 8
	s_andn2_b64 vcc, exec, s[0:1]
	s_nop 0
	v_writelane_b32 v247, s1, 9
	s_cbranch_vccnz .LBB0_703
	s_cmpk_gt_i32 s90, 0x5ff
	s_cbranch_scc1 .LBB0_703
	s_add_u32 s50, s92, 0xf000000
	v_and_b32_e32 v49, 15, v198
	s_addc_u32 s51, s93, 0
	s_waitcnt vmcnt(0)
	v_lshrrev_b32_e32 v0, 2, v198
	s_movk_i32 s0, 0xf0
	v_bfe_u32 v52, v198, 4, 2
	s_lshl_b32 s63, s90, 5
	v_lshrrev_b32_e32 v144, 4, v198
	v_and_or_b32 v145, v0, s0, v49
	v_lshlrev_b32_e32 v53, 3, v52
	v_bfe_u32 v0, v198, 2, 2
	s_and_b32 s0, s63, 0xffffff80
	v_or_b32_e32 v54, v53, v0
	v_or_b32_e32 v2, s0, v144
	s_movk_i32 s0, 0x1600
	v_mov_b64_e32 v[0:1], s[50:51]
	v_mad_i64_i32 v[0:1], s[0:1], v2, s0, v[0:1]
	s_lshl_b32 s0, s90, 8
	s_and_b32 s52, s0, 0x300
	s_mov_b32 s53, 0
	v_lshl_add_u64 v[0:1], v[0:1], 0, s[52:53]
	v_mov_b32_e32 v121, 0
	v_lshlrev_b32_e32 v120, 4, v49
	v_lshl_add_u64 v[36:37], v[0:1], 0, v[120:121]
	s_mov_b32 s0, 0x2c000
	v_add_co_u32_e32 v24, vcc, s0, v36
	s_mov_b32 s0, 0x58000
	s_nop 0
	v_addc_co_u32_e32 v25, vcc, 0, v37, vcc
	v_add_co_u32_e32 v38, vcc, s0, v36
	s_mov_b32 s0, 0x84000
	s_nop 0
	v_addc_co_u32_e32 v39, vcc, 0, v37, vcc
	v_add_co_u32_e32 v50, vcc, s0, v36
	global_load_dwordx4 v[0:3], v[36:37], off offset:1536
	global_load_dwordx4 v[4:7], v[36:37], off offset:2560
	global_load_dwordx4 v[8:11], v[36:37], off offset:3584
	v_addc_co_u32_e32 v51, vcc, 0, v37, vcc
	global_load_dwordx4 v[12:15], v[24:25], off offset:1536
	global_load_dwordx4 v[16:19], v[24:25], off offset:2560
	global_load_dwordx4 v[20:23], v[24:25], off offset:3584
	s_nop 0
	global_load_dwordx4 v[24:27], v[38:39], off offset:1536
	global_load_dwordx4 v[28:31], v[38:39], off offset:2560
	global_load_dwordx4 v[32:35], v[38:39], off offset:3584
	s_nop 0
	global_load_dwordx4 v[36:39], v[50:51], off offset:1536
	global_load_dwordx4 v[40:43], v[50:51], off offset:2560
	global_load_dwordx4 v[44:47], v[50:51], off offset:3584
	v_lshlrev_b32_e32 v50, 3, v198
	s_add_i32 s40, 0, 0x19800
	v_lshlrev_b32_e32 v51, 4, v52
	s_add_i32 s0, 0, 0x11000
	v_and_b32_e32 v50, 24, v50
	v_add_u32_e32 v146, s40, v51
	v_add_u32_e32 v147, 0, v51
	v_mul_u32_u24_e32 v51, 0x110, v54
	v_add3_u32 v149, s0, v50, v51
	v_add_u32_e32 v50, 1, v145
	v_cvt_f32_u32_e32 v150, v50
	v_sub_u32_e32 v50, 0x80, v145
	v_cvt_f32_i32_e32 v151, v50
	v_mul_u32_u24_e32 v50, 0x88, v144
	v_lshlrev_b32_e32 v51, 1, v50
	v_lshlrev_b32_e32 v50, 2, v52
	v_lshlrev_b32_e32 v48, 3, v49
	v_mul_u32_u24_e32 v154, 0x110, v49
	v_sub_u32_e32 v49, v145, v50
	v_sub_u32_e32 v52, 0, v49
	v_writelane_b32 v247, s94, 10
	v_add3_u32 v153, s0, v120, v51
	v_cmp_lt_i32_e64 s[0:1], 0, v49
	v_max_i32_e32 v49, v49, v52
	v_writelane_b32 v247, s95, 11
	v_cvt_f32_u32_e32 v156, v49
	v_or_b32_e32 v49, 1, v50
	v_writelane_b32 v247, s0, 12
	v_sub_u32_e32 v52, v145, v49
	v_mul_u32_u24_e32 v148, 0x110, v145
	v_writelane_b32 v247, s1, 13
	v_cmp_lt_i32_e64 s[0:1], 0, v52
	v_add3_u32 v155, s40, v148, v53
	v_sub_u32_e32 v53, 0, v52
	v_writelane_b32 v247, s0, 14
	v_max_i32_e32 v52, v52, v53
	v_cvt_f32_u32_e32 v157, v52
	v_writelane_b32 v247, s1, 15
	v_cmp_eq_u32_e64 s[0:1], v145, v50
	v_or_b32_e32 v52, 2, v50
	v_sub_u32_e32 v53, v145, v52
	v_writelane_b32 v247, s0, 16
	v_sub_u32_e32 v54, 0, v53
	s_mov_b64 s[60:61], s[86:87]
	v_writelane_b32 v247, s1, 17
	v_cmp_eq_u32_e64 s[0:1], v145, v49
	v_or_b32_e32 v49, 3, v50
	s_mov_b32 s64, s90
	v_writelane_b32 v247, s0, 18
	s_mov_b64 s[68:69], s[92:93]
	s_load_dwordx2 s[54:55], s[88:89], 0x90
	v_writelane_b32 v247, s1, 19
	v_cmp_lt_i32_e64 s[0:1], 0, v53
	v_max_i32_e32 v53, v53, v54
	v_cvt_f32_u32_e32 v158, v53
	v_writelane_b32 v247, s0, 20
	v_sub_u32_e32 v53, v145, v49
	v_sub_u32_e32 v54, 0, v53
	v_writelane_b32 v247, s1, 21
	v_cmp_lt_i32_e64 s[0:1], 0, v53
	v_max_i32_e32 v53, v53, v54
	v_cvt_f32_u32_e32 v159, v53
	v_writelane_b32 v247, s0, 22
	v_add3_u32 v188, s40, v120, v51
	s_load_dwordx4 s[40:43], s[88:89], 0x50
	v_writelane_b32 v247, s1, 23
	v_cmp_eq_u32_e64 s[0:1], v145, v49
	v_or_b32_e32 v49, 17, v50
	s_ashr_i32 s65, s64, 31
	v_writelane_b32 v247, s0, 24
	s_lshl_b64 s[56:57], s[64:65], 16
	s_add_i32 s52, s64, s60
	v_writelane_b32 v247, s1, 25
	v_cmp_eq_u32_e64 s[0:1], v145, v52
	v_or_b32_e32 v52, 16, v50
	v_sub_u32_e32 v53, v145, v52
	v_writelane_b32 v247, s0, 26
	v_sub_u32_e32 v54, 0, v53
	s_lshl_b32 s59, s52, 7
	v_writelane_b32 v247, s1, 27
	v_cmp_lt_i32_e64 s[0:1], 0, v53
	v_max_i32_e32 v53, v53, v54
	v_cvt_f32_u32_e32 v160, v53
	v_writelane_b32 v247, s0, 28
	v_sub_u32_e32 v53, v145, v49
	v_sub_u32_e32 v54, 0, v53
	v_writelane_b32 v247, s1, 29
	v_cmp_lt_i32_e64 s[0:1], 0, v53
	v_max_i32_e32 v53, v53, v54
	v_cvt_f32_u32_e32 v161, v53
	v_writelane_b32 v247, s0, 30
	v_lshlrev_b32_e32 v124, 1, v48
	v_mbcnt_lo_u32_b32 v48, -1, 0
	v_writelane_b32 v247, s1, 31
	v_cmp_eq_u32_e64 s[0:1], v145, v49
	v_or_b32_e32 v49, 19, v50
	s_mov_b32 s52, s64
	v_writelane_b32 v247, s0, 32
	v_add3_u32 v152, 0, v120, v51
	s_lshl_b32 s58, s60, 5
	v_writelane_b32 v247, s1, 33
	v_cmp_eq_u32_e64 s[0:1], v145, v52
	v_or_b32_e32 v52, 18, v50
	v_sub_u32_e32 v53, v145, v52
	v_writelane_b32 v247, s0, 34
	v_sub_u32_e32 v54, 0, v53
	v_mbcnt_hi_u32_b32 v189, -1, v48
	v_writelane_b32 v247, s1, 35
	v_cmp_lt_i32_e64 s[0:1], 0, v53
	v_max_i32_e32 v53, v53, v54
	v_cvt_f32_u32_e32 v162, v53
	v_writelane_b32 v247, s0, 36
	v_sub_u32_e32 v53, v145, v49
	v_sub_u32_e32 v54, 0, v53
	v_writelane_b32 v247, s1, 37
	v_cmp_lt_i32_e64 s[0:1], 0, v53
	v_max_i32_e32 v53, v53, v54
	v_cvt_f32_u32_e32 v163, v53
; __device__ __forceinline__ void ret_out_phase(const Params& p, LAS unsigned char* lds, int G) {
;     ...
;     const int trb = (8 * fq + (fr >> 2)) * 136 + 4 * (fr & 3);
;     const int il = 16 * wave + fr;
;     u32x4 pq[4], pk[4], pv[4];
;     ...
;             for (int n = 0; n < 8; ++n) { f32x4 pvv;
; #pragma unroll
;                 for (int e = 0; e < 4; ++e) { const int j = 16 * n + 4 * fq + e, dlt = il - j; const float coef = dlt > 0 ? ldf2 : ldb2; const float ex = __builtin_amdgcn_exp2f(coef * (float)(dlt > 0 ? dlt : -dlt)); pvv[e] = s[n][e] * (dlt == 0 ? 2.0f : ex); }
	v_writelane_b32 v247, s0, 38
	v_mov_b32_e32 v190, 0x358637bd
	s_mov_b32 s61, s64
	v_writelane_b32 v247, s1, 39
	v_cmp_eq_u32_e64 s[0:1], v145, v49
	v_or_b32_e32 v49, 33, v50
	s_nop 0
	v_writelane_b32 v247, s0, 40
	s_nop 1
	v_writelane_b32 v247, s1, 41
	v_cmp_eq_u32_e64 s[0:1], v145, v52
	v_or_b32_e32 v52, 32, v50
	v_sub_u32_e32 v53, v145, v52
	v_writelane_b32 v247, s0, 42
	v_sub_u32_e32 v54, 0, v53
	s_nop 0
	v_writelane_b32 v247, s1, 43
	v_cmp_lt_i32_e64 s[0:1], 0, v53
	v_max_i32_e32 v53, v53, v54
	v_cvt_f32_u32_e32 v164, v53
	v_writelane_b32 v247, s0, 44
	v_sub_u32_e32 v53, v145, v49
	v_sub_u32_e32 v54, 0, v53
	v_writelane_b32 v247, s1, 45
	v_cmp_lt_i32_e64 s[0:1], 0, v53
	v_max_i32_e32 v53, v53, v54
	v_cvt_f32_u32_e32 v165, v53
	v_writelane_b32 v247, s0, 46
	s_nop 1
	v_writelane_b32 v247, s1, 47
	v_cmp_eq_u32_e64 s[0:1], v145, v49
	v_or_b32_e32 v49, 35, v50
	s_nop 0
	v_writelane_b32 v247, s0, 48
	s_nop 1
	v_writelane_b32 v247, s1, 49
	v_cmp_eq_u32_e64 s[0:1], v145, v52
	v_or_b32_e32 v52, 34, v50
	v_sub_u32_e32 v53, v145, v52
	v_writelane_b32 v247, s0, 50
	v_sub_u32_e32 v54, 0, v53
	s_nop 0
	v_writelane_b32 v247, s1, 51
	v_cmp_lt_i32_e64 s[0:1], 0, v53
	v_max_i32_e32 v53, v53, v54
	v_cvt_f32_u32_e32 v166, v53
	v_writelane_b32 v247, s0, 52
	v_sub_u32_e32 v53, v145, v49
	v_sub_u32_e32 v54, 0, v53
	v_writelane_b32 v247, s1, 53
	v_cmp_lt_i32_e64 s[0:1], 0, v53
	v_max_i32_e32 v53, v53, v54
	v_cvt_f32_u32_e32 v167, v53
	v_writelane_b32 v247, s0, 54
	s_nop 1
	v_writelane_b32 v247, s1, 55
	v_cmp_eq_u32_e64 s[0:1], v145, v49
	v_or_b32_e32 v49, 49, v50
	s_nop 0
	v_writelane_b32 v247, s0, 56
	s_nop 1
	v_writelane_b32 v247, s1, 57
	v_cmp_eq_u32_e64 s[0:1], v145, v52
	v_or_b32_e32 v52, 48, v50
	v_sub_u32_e32 v53, v145, v52
	v_writelane_b32 v247, s0, 58
	v_sub_u32_e32 v54, 0, v53
	s_nop 0
	v_writelane_b32 v247, s1, 59
	v_cmp_lt_i32_e64 s[0:1], 0, v53
	v_max_i32_e32 v53, v53, v54
	v_cvt_f32_u32_e32 v168, v53
	v_writelane_b32 v247, s0, 60
	v_sub_u32_e32 v53, v145, v49
	v_sub_u32_e32 v54, 0, v53
	v_writelane_b32 v247, s1, 61
	v_cmp_lt_i32_e64 s[0:1], 0, v53
	v_max_i32_e32 v53, v53, v54
	v_cvt_f32_u32_e32 v169, v53
	v_writelane_b32 v247, s0, 62
	s_nop 1
	v_writelane_b32 v247, s1, 63
	v_cmp_eq_u32_e64 s[0:1], v145, v49
	v_or_b32_e32 v49, 51, v50
	s_nop 0
	v_writelane_b32 v246, s0, 0
	s_nop 1
	v_writelane_b32 v246, s1, 1
	v_cmp_eq_u32_e64 s[0:1], v145, v52
	v_or_b32_e32 v52, 50, v50
	v_sub_u32_e32 v53, v145, v52
	v_writelane_b32 v246, s0, 2
	v_sub_u32_e32 v54, 0, v53
	v_cmp_eq_u32_e64 s[70:71], v145, v52
	v_writelane_b32 v246, s1, 3
	v_cmp_lt_i32_e64 s[0:1], 0, v53
	v_max_i32_e32 v53, v53, v54
	v_cvt_f32_u32_e32 v170, v53
	v_sub_u32_e32 v53, v145, v49
	v_writelane_b32 v246, s0, 4
	v_sub_u32_e32 v54, 0, v53
	v_or_b32_e32 v52, 64, v50
	v_writelane_b32 v246, s1, 5
	v_cmp_lt_i32_e64 s[0:1], 0, v53
	v_max_i32_e32 v53, v53, v54
	v_cvt_f32_u32_e32 v171, v53
	v_sub_u32_e32 v53, v145, v52
	v_writelane_b32 v246, s0, 6
	v_sub_u32_e32 v54, 0, v53
	v_cmp_lt_i32_e64 s[72:73], 0, v53
	v_writelane_b32 v246, s1, 7
	v_cmp_eq_u32_e64 s[0:1], v145, v49
	v_or_b32_e32 v49, 0x41, v50
	v_max_i32_e32 v53, v53, v54
	v_cvt_f32_u32_e32 v172, v53
	v_sub_u32_e32 v53, v145, v49
	v_sub_u32_e32 v54, 0, v53
	v_cmp_lt_i32_e64 s[74:75], 0, v53
	v_max_i32_e32 v53, v53, v54
	v_cmp_eq_u32_e64 s[78:79], v145, v52
	v_or_b32_e32 v52, 0x42, v50
	v_cvt_f32_u32_e32 v173, v53
	v_sub_u32_e32 v53, v145, v52
	v_sub_u32_e32 v54, 0, v53
	v_cmp_eq_u32_e64 s[76:77], v145, v49
	v_or_b32_e32 v49, 0x43, v50
	v_cmp_lt_i32_e64 s[80:81], 0, v53
	v_max_i32_e32 v53, v53, v54
	v_cvt_f32_u32_e32 v174, v53
	v_sub_u32_e32 v53, v145, v49
	v_sub_u32_e32 v54, 0, v53
	v_cmp_lt_i32_e64 s[82:83], 0, v53
	v_max_i32_e32 v53, v53, v54
	v_cmp_eq_u32_e64 s[86:87], v145, v52
	v_or_b32_e32 v52, 0x50, v50
	v_cvt_f32_u32_e32 v175, v53
	v_sub_u32_e32 v53, v145, v52
	v_sub_u32_e32 v54, 0, v53
	v_cmp_eq_u32_e64 s[84:85], v145, v49
	v_or_b32_e32 v49, 0x51, v50
	v_cmp_lt_i32_e64 s[66:67], 0, v53
	v_max_i32_e32 v53, v53, v54
	v_cvt_f32_u32_e32 v176, v53
	v_sub_u32_e32 v53, v145, v49
	v_sub_u32_e32 v54, 0, v53
	v_cmp_lt_i32_e64 s[90:91], 0, v53
	v_max_i32_e32 v53, v53, v54
	v_cmp_eq_u32_e64 s[94:95], v145, v52
	v_or_b32_e32 v52, 0x52, v50
	v_cvt_f32_u32_e32 v177, v53
	v_sub_u32_e32 v53, v145, v52
	v_sub_u32_e32 v54, 0, v53
	v_cmp_eq_u32_e64 s[92:93], v145, v49
	v_or_b32_e32 v49, 0x53, v50
	v_cmp_lt_i32_e64 s[96:97], 0, v53
	v_max_i32_e32 v53, v53, v54
	v_cvt_f32_u32_e32 v178, v53
	v_sub_u32_e32 v53, v145, v49
	v_sub_u32_e32 v54, 0, v53
	v_cmp_lt_i32_e64 s[4:5], 0, v53
	v_max_i32_e32 v53, v53, v54
	v_cmp_eq_u32_e64 s[2:3], v145, v52
	v_or_b32_e32 v52, 0x60, v50
	v_cvt_f32_u32_e32 v179, v53
	v_sub_u32_e32 v53, v145, v52
	v_writelane_b32 v246, s0, 8
	v_sub_u32_e32 v54, 0, v53
	v_cmp_eq_u32_e64 s[6:7], v145, v49
	v_writelane_b32 v246, s1, 9
	v_or_b32_e32 v49, 0x61, v50
	v_cmp_lt_i32_e64 s[0:1], 0, v53
	v_max_i32_e32 v53, v53, v54
	v_cvt_f32_u32_e32 v180, v53
	v_sub_u32_e32 v53, v145, v49
	v_sub_u32_e32 v54, 0, v53
	v_cmp_lt_i32_e64 s[8:9], 0, v53
	v_max_i32_e32 v53, v53, v54
	v_cmp_eq_u32_e64 s[12:13], v145, v52
	v_or_b32_e32 v52, 0x62, v50
	v_cvt_f32_u32_e32 v181, v53
	v_sub_u32_e32 v53, v145, v52
	v_sub_u32_e32 v54, 0, v53
	v_cmp_eq_u32_e64 s[10:11], v145, v49
	v_or_b32_e32 v49, 0x63, v50
	v_cmp_lt_i32_e64 s[14:15], 0, v53
	v_max_i32_e32 v53, v53, v54
	v_cvt_f32_u32_e32 v182, v53
	v_sub_u32_e32 v53, v145, v49
	v_sub_u32_e32 v54, 0, v53
	v_cmp_lt_i32_e64 s[16:17], 0, v53
	v_max_i32_e32 v53, v53, v54
	v_cmp_eq_u32_e64 s[20:21], v145, v52
	v_or_b32_e32 v52, 0x70, v50
	v_cvt_f32_u32_e32 v183, v53
	v_sub_u32_e32 v53, v145, v52
	v_sub_u32_e32 v54, 0, v53
	v_cmp_eq_u32_e64 s[18:19], v145, v49
	v_or_b32_e32 v49, 0x71, v50
	v_cmp_lt_i32_e64 s[22:23], 0, v53
	v_max_i32_e32 v53, v53, v54
	v_cvt_f32_u32_e32 v184, v53
	v_sub_u32_e32 v53, v145, v49
	v_sub_u32_e32 v54, 0, v53
	v_cmp_lt_i32_e64 s[24:25], 0, v53
	v_max_i32_e32 v53, v53, v54
	v_cmp_eq_u32_e64 s[28:29], v145, v52
	v_or_b32_e32 v52, 0x72, v50
	v_cvt_f32_u32_e32 v185, v53
	v_sub_u32_e32 v53, v145, v52
	v_sub_u32_e32 v54, 0, v53
	v_cmp_eq_u32_e64 s[26:27], v145, v49
	v_or_b32_e32 v49, 0x73, v50
	v_cmp_lt_i32_e64 s[30:31], 0, v53
	v_max_i32_e32 v53, v53, v54
	v_cvt_f32_u32_e32 v186, v53
	v_sub_u32_e32 v53, v145, v49
	v_sub_u32_e32 v54, 0, v53
	v_cmp_lt_i32_e64 s[34:35], 0, v53
	v_max_i32_e32 v53, v53, v54
	v_cvt_f32_u32_e32 v187, v53
	v_cmp_eq_u32_e64 s[36:37], v145, v49
	v_lshlrev_b32_e32 v49, 8, v144
	v_cmp_eq_u32_e64 s[38:39], v145, v52
	v_or3_b32 v52, s56, v49, v120
	v_mov_b32_e32 v53, s57
	s_waitcnt lgkmcnt(0)
	v_lshl_add_u64 v[122:123], s[54:55], 0, v[52:53]
	s_ashr_i32 s55, s60, 31
	s_mov_b32 s54, s60
	s_lshl_b64 s[54:55], s[54:55], 16
	s_lshl_b32 s60, s60, 7
	v_lshlrev_b32_e32 v120, 1, v50
	v_writelane_b32 v246, s52, 10
	s_nop 1
	v_writelane_b32 v246, s53, 11
	s_waitcnt vmcnt(0)
	s_branch .LBB0_698

; #define LAS __attribute__((address_space(3)))
; #define R3_ISSUE(u_) do { const bf16_t* src_ = proj + (size_t)(((u_) >> 2) * 128 + stok) * DIN + 768 + ((u_) & 3) * 128 + sdch * 8; \
;         _Pragma("unroll") for (int i_ = 0; i_ < 4; ++i_) { pq[i_] = *(const u32x4*)(src_ + (size_t)i_ * 32 * DIN); pk[i_] = *(const u32x4*)(src_ + 512 + (size_t)i_ * 32 * DIN); pv[i_] = *(const u32x4*)(src_ + 1024 + (size_t)i_ * 32 * DIN); } } while (0)
; __device__ __forceinline__ void ret_out_phase(const Params& p, LAS unsigned char* lds, int G) {
;     ...
;         const int c = unit >> 2, h = unit & 3, row0 = c * 128;
;         const float ldf = p.in[10][h], ldb = p.in[11][h]; const float ldf2 = ldf * 1.4426950408889634f, ldb2 = ldb * 1.4426950408889634f;
;         __syncthreads();
; #pragma unroll
;         for (int i = 0; i < 4; ++i) {
;             const int tok = stok + 32 * i;
;             *(LAS u32x4*)(Ql + tok * 136 + sdch * 8) = pq[i]; *(LAS u32x4*)(Kl + tok * 136 + sdch * 8) = pk[i]; *(LAS u32x4*)(Vl + tok * 136 + sdch * 8) = pv[i];
;         }
;         __syncthreads();
;         if (unit + G < (T / 128) * 4) R3_ISSUE(unit + G);
.LBB0_698:
	s_and_b32 s64, s61, 3
	s_lshl_b32 s52, s64, 2
	v_mov_b32_e32 v48, s52
	s_load_dword s98, s[40:41], s52
	s_load_dword s99, s[42:43], s52
	s_barrier
	ds_write_b128 v152, v[0:3]
	ds_write_b128 v152, v[4:7] offset:34816
	ds_write_b128 v153, v[8:11]
	ds_write_b128 v152, v[12:15] offset:8704
	ds_write_b128 v152, v[16:19] offset:43520
	ds_write_b128 v153, v[20:23] offset:8704
	ds_write_b128 v152, v[24:27] offset:17408
	ds_write_b128 v152, v[28:31] offset:52224
	ds_write_b128 v153, v[32:35] offset:17408
	ds_write_b128 v152, v[36:39] offset:26112
	ds_write_b128 v152, v[40:43] offset:60928
	ds_write_b128 v153, v[44:47] offset:26112
	s_waitcnt lgkmcnt(0)
	v_mov_b32_e32 v192, s98
	v_mov_b32_e32 v191, s99
	s_barrier
	s_load_dwordx2 s[56:57], s[88:89], 0xa8
	s_mov_b64 vcc, -1
	s_waitcnt lgkmcnt(0)
	s_add_i32 s61, s61, s56
	s_cmpk_gt_i32 s61, 0x5ff
	s_cselect_b64 s[56:57], -1, 0
	s_cmpk_lt_i32 s61, 0x600
	s_cbranch_scc1 .LBB0_700
	s_add_i32 s62, s63, s58
	s_mov_b64 vcc, 0
